# P1 in-projection output stores sc1 nt (on top of P8 deferred stores + sc1 nt)
# speedup vs baseline: 1.0026x; 1.0026x over previous
.LBB0_347:
	s_cmp_lt_u32 s39, 4
	v_cvt_pk_bf16_f32 v184, v124, v125
	v_cvt_pk_bf16_f32 v185, v126, v127
	v_cvt_pk_bf16_f32 v186, v120, v121
	v_cvt_pk_bf16_f32 v187, v122, v123
	v_cvt_pk_bf16_f32 v188, v116, v117
	v_cvt_pk_bf16_f32 v189, v118, v119
	v_cvt_pk_bf16_f32 v190, v112, v113
	v_cvt_pk_bf16_f32 v191, v114, v115
	v_cvt_pk_bf16_f32 v180, v108, v109
	v_cvt_pk_bf16_f32 v181, v110, v111
	v_cvt_pk_bf16_f32 v182, v104, v105
	v_cvt_pk_bf16_f32 v183, v106, v107
	v_cvt_pk_bf16_f32 v176, v100, v101
	v_cvt_pk_bf16_f32 v177, v102, v103
	v_cvt_pk_bf16_f32 v178, v96, v97
	v_cvt_pk_bf16_f32 v179, v98, v99
	v_cvt_pk_bf16_f32 v172, v92, v93
	v_cvt_pk_bf16_f32 v173, v94, v95
	v_cvt_pk_bf16_f32 v174, v88, v89
	v_cvt_pk_bf16_f32 v175, v90, v91
	v_cvt_pk_bf16_f32 v168, v84, v85
	v_cvt_pk_bf16_f32 v169, v86, v87
	v_cvt_pk_bf16_f32 v170, v80, v81
	v_cvt_pk_bf16_f32 v171, v82, v83
	v_cvt_pk_bf16_f32 v164, v76, v77
	v_cvt_pk_bf16_f32 v165, v78, v79
	v_cvt_pk_bf16_f32 v166, v72, v73
	v_cvt_pk_bf16_f32 v167, v74, v75
	v_cvt_pk_bf16_f32 v160, v68, v69
	v_cvt_pk_bf16_f32 v161, v70, v71
	v_cvt_pk_bf16_f32 v162, v64, v65
	v_cvt_pk_bf16_f32 v163, v66, v67
	v_cvt_pk_bf16_f32 v156, v60, v61
	v_cvt_pk_bf16_f32 v157, v62, v63
	v_cvt_pk_bf16_f32 v158, v56, v57
	v_cvt_pk_bf16_f32 v159, v58, v59
	v_cvt_pk_bf16_f32 v152, v52, v53
	v_cvt_pk_bf16_f32 v153, v54, v55
	v_cvt_pk_bf16_f32 v154, v44, v45
	v_cvt_pk_bf16_f32 v155, v46, v47
	v_cvt_pk_bf16_f32 v148, v48, v49
	v_cvt_pk_bf16_f32 v149, v50, v51
	v_cvt_pk_bf16_f32 v150, v40, v41
	v_cvt_pk_bf16_f32 v151, v42, v43
	v_cvt_pk_bf16_f32 v144, v36, v37
	v_cvt_pk_bf16_f32 v145, v38, v39
	v_cvt_pk_bf16_f32 v146, v28, v29
	v_cvt_pk_bf16_f32 v147, v30, v31
	v_cvt_pk_bf16_f32 v140, v32, v33
	v_cvt_pk_bf16_f32 v141, v34, v35
	v_cvt_pk_bf16_f32 v142, v24, v25
	v_cvt_pk_bf16_f32 v143, v26, v27
	v_cvt_pk_bf16_f32 v136, v20, v21
	v_cvt_pk_bf16_f32 v137, v22, v23
	v_cvt_pk_bf16_f32 v138, v12, v13
	v_cvt_pk_bf16_f32 v139, v14, v15
	v_cvt_pk_bf16_f32 v132, v16, v17
	v_cvt_pk_bf16_f32 v133, v18, v19
	v_cvt_pk_bf16_f32 v134, v8, v9
	v_cvt_pk_bf16_f32 v135, v10, v11
	v_cvt_pk_bf16_f32 v128, v4, v5
	v_cvt_pk_bf16_f32 v129, v6, v7
	v_cvt_pk_bf16_f32 v130, v0, v1
	v_cvt_pk_bf16_f32 v131, v2, v3
	s_cbranch_scc1 .LBB0_349
	v_lshlrev_b32_e32 v200, 6, v216
	v_and_b32_e32 v215, 0x5c00, v200
	s_ashr_i32 s26, s41, 5
	v_add_u32_e32 v200, s26, v215
	v_add_u32_e32 v213, 0x2000, v200
	v_mad_i64_i32 v[218:219], s[26:27], v200, s70, v[202:203]
	v_mad_i64_i32 v[228:229], s[26:27], v213, s70, v[202:203]
	v_add_u32_e32 v213, 1, v200
	global_store_dwordx4 v[218:219], v[184:187], off sc1 nt
	global_store_dwordx4 v[228:229], v[188:191], off sc1 nt
	global_store_dwordx4 v[218:219], v[180:183], off offset:512 sc1 nt
	global_store_dwordx4 v[228:229], v[176:179], off offset:512 sc1 nt
	v_mad_i64_i32 v[218:219], s[26:27], v213, s70, v[202:203]
	v_add_u32_e32 v200, 0x2001, v200
	global_store_dwordx4 v[218:219], v[172:175], off sc1 nt
	v_mad_i64_i32 v[218:219], s[26:27], v200, s70, v[202:203]
	v_or_b32_e32 v200, 48, v214
	v_ashrrev_i32_e32 v213, 5, v200
	global_store_dwordx4 v[218:219], v[168:171], off sc1 nt
	v_add_u32_e32 v217, v213, v215
	v_mov_b64_e32 v[218:219], s[14:15]
	v_lshlrev_b32_e32 v200, 5, v200
	v_mad_i64_i32 v[228:229], s[26:27], v217, s70, v[218:219]
	v_and_b32_e32 v200, 0x3e0, v200
	v_lshl_add_u64 v[228:229], v[228:229], 0, v[200:201]
	v_mov_b32_e32 v213, v201
	v_lshl_add_u64 v[228:229], v[228:229], 0, v[212:213]
	v_add_u32_e32 v217, 0x2000, v217
	global_store_dwordx4 v[228:229], v[164:167], off sc1 nt
	v_mad_i64_i32 v[228:229], s[26:27], v217, s70, v[218:219]
	s_add_i32 s26, s41, 0x80
	v_lshl_add_u64 v[228:229], v[228:229], 0, v[200:201]
	s_ashr_i32 s26, s26, 5
	v_lshl_add_u64 v[228:229], v[228:229], 0, v[212:213]
	v_add_u32_e32 v200, s26, v215
	global_store_dwordx4 v[228:229], v[160:163], off sc1 nt
	v_mad_i64_i32 v[228:229], s[26:27], v200, s70, v[202:203]
	v_add_u32_e32 v200, 0x2000, v200
	global_store_dwordx4 v[228:229], v[156:159], off sc1 nt
	v_mad_i64_i32 v[228:229], s[26:27], v200, s70, v[202:203]
	v_add_u32_e32 v200, 0x90, v214
	v_ashrrev_i32_e32 v217, 5, v200
	v_add_u32_e32 v217, v217, v215
	v_lshlrev_b32_e32 v200, 5, v200
	global_store_dwordx4 v[228:229], v[152:155], off sc1 nt
	v_mad_i64_i32 v[228:229], s[26:27], v217, s70, v[218:219]
	v_and_b32_e32 v200, 0x3e0, v200
	v_lshl_add_u64 v[228:229], v[228:229], 0, v[200:201]
	v_lshl_add_u64 v[228:229], v[228:229], 0, v[212:213]
	v_add_u32_e32 v217, 0x2000, v217
	global_store_dwordx4 v[228:229], v[148:151], off sc1 nt
	v_mad_i64_i32 v[228:229], s[26:27], v217, s70, v[218:219]
	s_addk_i32 s41, 0xa0
	v_lshl_add_u64 v[228:229], v[228:229], 0, v[200:201]
	s_ashr_i32 s26, s41, 5
	v_lshl_add_u64 v[228:229], v[228:229], 0, v[212:213]
	v_add_u32_e32 v200, s26, v215
	global_store_dwordx4 v[228:229], v[144:147], off sc1 nt
	v_mad_i64_i32 v[228:229], s[26:27], v200, s70, v[202:203]
	v_add_u32_e32 v200, 0x2000, v200
	global_store_dwordx4 v[228:229], v[140:143], off sc1 nt
	v_mad_i64_i32 v[228:229], s[26:27], v200, s70, v[202:203]
	v_add_u32_e32 v200, 0xb0, v214
	v_ashrrev_i32_e32 v217, 5, v200
	v_add_u32_e32 v215, v217, v215
	global_store_dwordx4 v[228:229], v[136:139], off sc1 nt
	v_mad_i64_i32 v[228:229], s[26:27], v215, s70, v[218:219]
	v_lshlrev_b32_e32 v200, 5, v200
	v_add_u32_e32 v215, 0x2000, v215
	v_and_b32_e32 v200, 0x3e0, v200
	v_mad_i64_i32 v[218:219], s[26:27], v215, s70, v[218:219]
	v_lshl_add_u64 v[228:229], v[228:229], 0, v[200:201]
	v_lshl_add_u64 v[218:219], v[218:219], 0, v[200:201]
	v_lshl_add_u64 v[228:229], v[228:229], 0, v[212:213]
	v_lshl_add_u64 v[218:219], v[218:219], 0, v[212:213]
	s_mov_b64 s[46:47], 0
	global_store_dwordx4 v[228:229], v[132:135], off sc1 nt
	global_store_dwordx4 v[218:219], v[128:131], off sc1 nt
.LBB0_349:
	s_andn2_b64 vcc, exec, s[46:47]
	s_cbranch_vccnz .LBB0_351
	v_readlane_b32 s46, v254, 43
	s_cmp_eq_u32 s39, 2
	v_readlane_b32 s26, v254, 42
	v_readlane_b32 s47, v254, 44
	s_cselect_b32 s27, s26, s47
	v_readlane_b32 s26, v254, 41
	s_cselect_b32 s26, s26, s46
	v_lshlrev_b32_e32 v200, 1, v216
	v_ashrrev_i32_e32 v215, 31, v214
	v_lshl_add_u64 v[218:219], s[26:27], 0, v[200:201]
	v_lshlrev_b64 v[228:229], 10, v[214:215]
	v_lshl_add_u64 v[228:229], v[218:219], 0, v[228:229]
	global_store_dwordx4 v[228:229], v[184:187], off sc1 nt
	global_store_dwordx4 v[228:229], v[188:191], off offset:256 sc1 nt
	s_nop 0
	v_or_b32_e32 v184, 16, v214
	v_ashrrev_i32_e32 v185, 31, v184
	v_lshlrev_b64 v[184:185], 10, v[184:185]
	v_lshl_add_u64 v[184:185], v[218:219], 0, v[184:185]
	global_store_dwordx4 v[184:185], v[180:183], off sc1 nt
	global_store_dwordx4 v[184:185], v[176:179], off offset:256 sc1 nt
	s_nop 1
	v_or_b32_e32 v176, 32, v214
	v_ashrrev_i32_e32 v177, 31, v176
	v_lshlrev_b64 v[176:177], 10, v[176:177]
	v_lshl_add_u64 v[176:177], v[218:219], 0, v[176:177]
	global_store_dwordx4 v[176:177], v[172:175], off sc1 nt
	global_store_dwordx4 v[176:177], v[168:171], off offset:256 sc1 nt
	s_nop 1
	v_or_b32_e32 v168, 48, v214
	v_ashrrev_i32_e32 v169, 31, v168
	v_lshlrev_b64 v[168:169], 10, v[168:169]
	v_lshl_add_u64 v[168:169], v[218:219], 0, v[168:169]
	global_store_dwordx4 v[168:169], v[164:167], off sc1 nt
	global_store_dwordx4 v[168:169], v[160:163], off offset:256 sc1 nt
	s_nop 1
	v_add_co_u32_e32 v162, vcc, s71, v228
	v_lshl_add_u64 v[160:161], v[228:229], 0, s[16:17]
	s_nop 0
	v_addc_co_u32_e32 v163, vcc, 0, v229, vcc
	global_store_dwordx4 v[162:163], v[156:159], off sc1 nt
	global_store_dwordx4 v[160:161], v[152:155], off offset:256 sc1 nt
	s_nop 1
	v_add_co_u32_e32 v154, vcc, s74, v228
	v_lshl_add_u64 v[152:153], v[228:229], 0, s[18:19]
	s_nop 0
	v_addc_co_u32_e32 v155, vcc, 0, v229, vcc
	global_store_dwordx4 v[154:155], v[148:151], off sc1 nt
	global_store_dwordx4 v[152:153], v[144:147], off offset:256 sc1 nt
	s_nop 1
	v_add_co_u32_e32 v146, vcc, s75, v228
	v_lshl_add_u64 v[144:145], v[228:229], 0, s[20:21]
	s_nop 0
	v_addc_co_u32_e32 v147, vcc, 0, v229, vcc
	global_store_dwordx4 v[146:147], v[140:143], off sc1 nt
	global_store_dwordx4 v[144:145], v[136:139], off offset:256 sc1 nt
	s_nop 1
	v_add_co_u32_e32 v138, vcc, s78, v228
	v_lshl_add_u64 v[136:137], v[228:229], 0, s[22:23]
	s_nop 0
	v_addc_co_u32_e32 v139, vcc, 0, v229, vcc
	global_store_dwordx4 v[138:139], v[132:135], off sc1 nt
	global_store_dwordx4 v[136:137], v[128:131], off offset:256 sc1 nt

.LBB0_352:
	v_lshlrev_b32_e32 v134, 7, v214
	v_and_or_b32 v128, v134, s79, v224
	v_lshlrev_b32_e32 v200, 2, v128
	global_load_dwordx4 v[184:187], v200, s[8:9] offset:16
	global_load_dwordx4 v[188:191], v200, s[8:9]
	v_lshl_add_u64 v[128:129], s[8:9], 0, v[200:201]
	v_add_co_u32_e32 v132, vcc, s60, v128
	v_lshl_add_u64 v[130:131], v[128:129], 0, s[30:31]
	s_nop 0
	v_addc_co_u32_e32 v133, vcc, 0, v129, vcc
	global_load_dwordx4 v[180:183], v[132:133], off
	global_load_dwordx4 v[176:179], v[130:131], off offset:16
	v_add_co_u32_e32 v132, vcc, s62, v128
	v_lshl_add_u64 v[130:131], v[128:129], 0, s[34:35]
	s_nop 0
	v_addc_co_u32_e32 v133, vcc, 0, v129, vcc
	global_load_dwordx4 v[172:175], v[132:133], off
	global_load_dwordx4 v[168:171], v[130:131], off offset:16
	v_lshl_add_u64 v[130:131], v[128:129], 0, s[36:37]
	v_add_co_u32_e32 v128, vcc, s63, v128
	v_readlane_b32 s26, v254, 45
	s_nop 0
	v_addc_co_u32_e32 v129, vcc, 0, v129, vcc
	global_load_dwordx4 v[164:167], v[128:129], off
	global_load_dwordx4 v[160:163], v[130:131], off offset:16
	v_add_u32_e32 v128, 0x4000, v134
	v_and_or_b32 v128, v128, s79, v224
	v_lshlrev_b32_e32 v200, 2, v128
	global_load_dwordx4 v[152:155], v200, s[8:9] offset:16
	global_load_dwordx4 v[156:159], v200, s[8:9]
	v_lshl_add_u64 v[128:129], s[8:9], 0, v[200:201]
	v_add_co_u32_e32 v132, vcc, s60, v128
	s_cmp_lt_u32 s92, 2
	v_readlane_b32 s27, v254, 46
	v_readlane_b32 s39, v254, 40
	v_addc_co_u32_e32 v133, vcc, 0, v129, vcc
	s_cselect_b32 s27, s27, s39
	v_readlane_b32 s39, v254, 39
	v_lshl_add_u64 v[130:131], v[128:129], 0, s[30:31]
	global_load_dwordx4 v[148:151], v[132:133], off
	global_load_dwordx4 v[144:147], v[130:131], off offset:16
	v_add_co_u32_e32 v132, vcc, s62, v128
	s_cselect_b32 s26, s26, s39
	v_lshl_add_u64 v[130:131], v[128:129], 0, s[34:35]
	v_addc_co_u32_e32 v133, vcc, 0, v129, vcc
	v_lshlrev_b32_e32 v200, 1, v216
	v_ashrrev_i32_e32 v215, 31, v214
	global_load_dwordx4 v[140:143], v[132:133], off
	global_load_dwordx4 v[136:139], v[130:131], off offset:16
	v_lshl_add_u64 v[130:131], v[128:129], 0, s[36:37]
	v_add_co_u32_e32 v128, vcc, s63, v128
	v_lshl_add_u64 v[218:219], s[26:27], 0, v[200:201]
	v_lshlrev_b64 v[216:217], 10, v[214:215]
	v_addc_co_u32_e32 v129, vcc, 0, v129, vcc
	v_lshl_add_u64 v[216:217], v[218:219], 0, v[216:217]
	global_load_dwordx4 v[132:135], v[128:129], off
	s_nop 0
	global_load_dwordx4 v[128:131], v[130:131], off offset:16
	s_waitcnt vmcnt(0)
	v_pk_mul_f32 v[228:229], v[124:125], v[188:189] op_sel:[1,1] op_sel_hi:[1,0]
	s_nop 0
	v_pk_fma_f32 v[230:231], v[124:125], v[188:189], v[228:229] neg_lo:[0,0,1] neg_hi:[0,0,1]
	v_pk_fma_f32 v[124:125], v[124:125], v[188:189], v[228:229] op_sel_hi:[0,1,1]
	v_mov_b32_e32 v124, v127
	v_pk_mul_f32 v[228:229], v[124:125], v[190:191] op_sel:[0,1] op_sel_hi:[0,0]
	v_pk_fma_f32 v[232:233], v[126:127], v[190:191], v[228:229] neg_lo:[0,0,1] neg_hi:[0,0,1]
	v_pk_fma_f32 v[126:127], v[126:127], v[190:191], v[228:229] op_sel_hi:[0,1,1]
	v_pk_mul_f32 v[228:229], v[120:121], v[184:185] op_sel:[1,1] op_sel_hi:[1,0]
	s_nop 0
	v_pk_fma_f32 v[234:235], v[120:121], v[184:185], v[228:229] neg_lo:[0,0,1] neg_hi:[0,0,1]
	v_pk_fma_f32 v[228:229], v[120:121], v[184:185], v[228:229] op_sel_hi:[0,1,1]
	v_mov_b32_e32 v120, v123
	v_pk_mul_f32 v[120:121], v[120:121], v[186:187] op_sel:[0,1] op_sel_hi:[0,0]
	v_pk_fma_f32 v[236:237], v[122:123], v[186:187], v[120:121] neg_lo:[0,0,1] neg_hi:[0,0,1]
	v_pk_fma_f32 v[122:123], v[122:123], v[186:187], v[120:121] op_sel_hi:[0,1,1]
	v_cvt_pk_bf16_f32 v120, v230, v125
	v_cvt_pk_bf16_f32 v121, v232, v127
	v_cvt_pk_bf16_f32 v122, v234, v229
	v_cvt_pk_bf16_f32 v123, v236, v123
	global_store_dwordx4 v[216:217], v[120:123], off sc1 nt
	s_nop 1
	v_pk_mul_f32 v[120:121], v[116:117], v[188:189] op_sel:[1,1] op_sel_hi:[1,0]
	s_nop 0
	v_pk_fma_f32 v[122:123], v[116:117], v[188:189], v[120:121] neg_lo:[0,0,1] neg_hi:[0,0,1]
	v_pk_fma_f32 v[116:117], v[116:117], v[188:189], v[120:121] op_sel_hi:[0,1,1]
	v_mov_b32_e32 v116, v119
	v_pk_mul_f32 v[120:121], v[116:117], v[190:191] op_sel:[0,1] op_sel_hi:[0,0]
	v_pk_fma_f32 v[124:125], v[118:119], v[190:191], v[120:121] neg_lo:[0,0,1] neg_hi:[0,0,1]
	v_pk_fma_f32 v[118:119], v[118:119], v[190:191], v[120:121] op_sel_hi:[0,1,1]
	v_pk_mul_f32 v[120:121], v[112:113], v[184:185] op_sel:[1,1] op_sel_hi:[1,0]
	s_nop 0
	v_pk_fma_f32 v[126:127], v[112:113], v[184:185], v[120:121] neg_lo:[0,0,1] neg_hi:[0,0,1]
	v_pk_fma_f32 v[120:121], v[112:113], v[184:185], v[120:121] op_sel_hi:[0,1,1]
	v_mov_b32_e32 v112, v115
	v_pk_mul_f32 v[112:113], v[112:113], v[186:187] op_sel:[0,1] op_sel_hi:[0,0]
	v_pk_fma_f32 v[184:185], v[114:115], v[186:187], v[112:113] neg_lo:[0,0,1] neg_hi:[0,0,1]
	v_pk_fma_f32 v[114:115], v[114:115], v[186:187], v[112:113] op_sel_hi:[0,1,1]
	v_cvt_pk_bf16_f32 v112, v122, v117
	v_cvt_pk_bf16_f32 v113, v124, v119
	v_cvt_pk_bf16_f32 v114, v126, v121
	v_cvt_pk_bf16_f32 v115, v184, v115
	global_store_dwordx4 v[216:217], v[112:115], off offset:256 sc1 nt
	s_nop 1
	v_pk_mul_f32 v[114:115], v[108:109], v[180:181] op_sel:[1,1] op_sel_hi:[1,0]
	v_or_b32_e32 v112, 16, v214
	v_pk_fma_f32 v[116:117], v[108:109], v[180:181], v[114:115] neg_lo:[0,0,1] neg_hi:[0,0,1]
	v_pk_fma_f32 v[108:109], v[108:109], v[180:181], v[114:115] op_sel_hi:[0,1,1]
	v_mov_b32_e32 v108, v111
	v_pk_mul_f32 v[114:115], v[108:109], v[182:183] op_sel:[0,1] op_sel_hi:[0,0]
	v_pk_fma_f32 v[118:119], v[110:111], v[182:183], v[114:115] neg_lo:[0,0,1] neg_hi:[0,0,1]
	v_pk_fma_f32 v[110:111], v[110:111], v[182:183], v[114:115] op_sel_hi:[0,1,1]
	v_pk_mul_f32 v[114:115], v[104:105], v[176:177] op_sel:[1,1] op_sel_hi:[1,0]
	v_ashrrev_i32_e32 v113, 31, v112
	v_pk_fma_f32 v[120:121], v[104:105], v[176:177], v[114:115] neg_lo:[0,0,1] neg_hi:[0,0,1]
	v_pk_fma_f32 v[114:115], v[104:105], v[176:177], v[114:115] op_sel_hi:[0,1,1]
	v_mov_b32_e32 v104, v107
	v_pk_mul_f32 v[104:105], v[104:105], v[178:179] op_sel:[0,1] op_sel_hi:[0,0]
	v_lshlrev_b64 v[112:113], 10, v[112:113]
	v_pk_fma_f32 v[122:123], v[106:107], v[178:179], v[104:105] neg_lo:[0,0,1] neg_hi:[0,0,1]
	v_pk_fma_f32 v[106:107], v[106:107], v[178:179], v[104:105] op_sel_hi:[0,1,1]
	v_lshl_add_u64 v[112:113], v[218:219], 0, v[112:113]
	v_cvt_pk_bf16_f32 v104, v116, v109
	v_cvt_pk_bf16_f32 v105, v118, v111
	v_cvt_pk_bf16_f32 v106, v120, v115
	v_cvt_pk_bf16_f32 v107, v122, v107
	global_store_dwordx4 v[112:113], v[104:107], off sc1 nt
	s_nop 1
	v_pk_mul_f32 v[104:105], v[100:101], v[180:181] op_sel:[1,1] op_sel_hi:[1,0]
	s_nop 0
	v_pk_fma_f32 v[106:107], v[100:101], v[180:181], v[104:105] neg_lo:[0,0,1] neg_hi:[0,0,1]
	v_pk_fma_f32 v[100:101], v[100:101], v[180:181], v[104:105] op_sel_hi:[0,1,1]
	v_mov_b32_e32 v100, v103
	v_pk_mul_f32 v[104:105], v[100:101], v[182:183] op_sel:[0,1] op_sel_hi:[0,0]
	v_pk_fma_f32 v[108:109], v[102:103], v[182:183], v[104:105] neg_lo:[0,0,1] neg_hi:[0,0,1]
	v_pk_fma_f32 v[102:103], v[102:103], v[182:183], v[104:105] op_sel_hi:[0,1,1]
	v_pk_mul_f32 v[104:105], v[96:97], v[176:177] op_sel:[1,1] op_sel_hi:[1,0]
	s_nop 0
	v_pk_fma_f32 v[110:111], v[96:97], v[176:177], v[104:105] neg_lo:[0,0,1] neg_hi:[0,0,1]
	v_pk_fma_f32 v[104:105], v[96:97], v[176:177], v[104:105] op_sel_hi:[0,1,1]
	v_mov_b32_e32 v96, v99
	v_pk_mul_f32 v[96:97], v[96:97], v[178:179] op_sel:[0,1] op_sel_hi:[0,0]
	v_pk_fma_f32 v[114:115], v[98:99], v[178:179], v[96:97] neg_lo:[0,0,1] neg_hi:[0,0,1]
	v_pk_fma_f32 v[98:99], v[98:99], v[178:179], v[96:97] op_sel_hi:[0,1,1]
	v_cvt_pk_bf16_f32 v96, v106, v101
	v_cvt_pk_bf16_f32 v97, v108, v103
	v_cvt_pk_bf16_f32 v98, v110, v105
	v_cvt_pk_bf16_f32 v99, v114, v99
	global_store_dwordx4 v[112:113], v[96:99], off offset:256 sc1 nt
	s_nop 1
	v_pk_mul_f32 v[98:99], v[92:93], v[172:173] op_sel:[1,1] op_sel_hi:[1,0]
	v_or_b32_e32 v96, 32, v214
	v_pk_fma_f32 v[100:101], v[92:93], v[172:173], v[98:99] neg_lo:[0,0,1] neg_hi:[0,0,1]
	v_pk_fma_f32 v[92:93], v[92:93], v[172:173], v[98:99] op_sel_hi:[0,1,1]
	v_mov_b32_e32 v92, v95
	v_pk_mul_f32 v[98:99], v[92:93], v[174:175] op_sel:[0,1] op_sel_hi:[0,0]
	v_pk_fma_f32 v[102:103], v[94:95], v[174:175], v[98:99] neg_lo:[0,0,1] neg_hi:[0,0,1]
	v_pk_fma_f32 v[94:95], v[94:95], v[174:175], v[98:99] op_sel_hi:[0,1,1]
	v_pk_mul_f32 v[98:99], v[88:89], v[168:169] op_sel:[1,1] op_sel_hi:[1,0]
	v_ashrrev_i32_e32 v97, 31, v96
	v_pk_fma_f32 v[104:105], v[88:89], v[168:169], v[98:99] neg_lo:[0,0,1] neg_hi:[0,0,1]
	v_pk_fma_f32 v[98:99], v[88:89], v[168:169], v[98:99] op_sel_hi:[0,1,1]
	v_mov_b32_e32 v88, v91
	v_pk_mul_f32 v[88:89], v[88:89], v[170:171] op_sel:[0,1] op_sel_hi:[0,0]
	v_lshlrev_b64 v[96:97], 10, v[96:97]
	v_pk_fma_f32 v[106:107], v[90:91], v[170:171], v[88:89] neg_lo:[0,0,1] neg_hi:[0,0,1]
	v_pk_fma_f32 v[90:91], v[90:91], v[170:171], v[88:89] op_sel_hi:[0,1,1]
	v_lshl_add_u64 v[96:97], v[218:219], 0, v[96:97]
	v_cvt_pk_bf16_f32 v88, v100, v93
	v_cvt_pk_bf16_f32 v89, v102, v95
	v_cvt_pk_bf16_f32 v90, v104, v99
	v_cvt_pk_bf16_f32 v91, v106, v91
	global_store_dwordx4 v[96:97], v[88:91], off sc1 nt
	s_nop 1
	v_pk_mul_f32 v[88:89], v[84:85], v[172:173] op_sel:[1,1] op_sel_hi:[1,0]
	s_nop 0
	v_pk_fma_f32 v[90:91], v[84:85], v[172:173], v[88:89] neg_lo:[0,0,1] neg_hi:[0,0,1]
	v_pk_fma_f32 v[84:85], v[84:85], v[172:173], v[88:89] op_sel_hi:[0,1,1]
	v_mov_b32_e32 v84, v87
	v_pk_mul_f32 v[88:89], v[84:85], v[174:175] op_sel:[0,1] op_sel_hi:[0,0]
	v_pk_fma_f32 v[92:93], v[86:87], v[174:175], v[88:89] neg_lo:[0,0,1] neg_hi:[0,0,1]
	v_pk_fma_f32 v[86:87], v[86:87], v[174:175], v[88:89] op_sel_hi:[0,1,1]
	v_pk_mul_f32 v[88:89], v[80:81], v[168:169] op_sel:[1,1] op_sel_hi:[1,0]
	s_nop 0
	v_pk_fma_f32 v[94:95], v[80:81], v[168:169], v[88:89] neg_lo:[0,0,1] neg_hi:[0,0,1]
	v_pk_fma_f32 v[88:89], v[80:81], v[168:169], v[88:89] op_sel_hi:[0,1,1]
	v_mov_b32_e32 v80, v83
	v_pk_mul_f32 v[80:81], v[80:81], v[170:171] op_sel:[0,1] op_sel_hi:[0,0]
	v_pk_fma_f32 v[98:99], v[82:83], v[170:171], v[80:81] neg_lo:[0,0,1] neg_hi:[0,0,1]
	v_pk_fma_f32 v[82:83], v[82:83], v[170:171], v[80:81] op_sel_hi:[0,1,1]
	v_cvt_pk_bf16_f32 v80, v90, v85
	v_cvt_pk_bf16_f32 v81, v92, v87
	v_cvt_pk_bf16_f32 v82, v94, v89
	v_cvt_pk_bf16_f32 v83, v98, v83
	global_store_dwordx4 v[96:97], v[80:83], off offset:256 sc1 nt
	s_nop 1
	v_pk_mul_f32 v[82:83], v[76:77], v[164:165] op_sel:[1,1] op_sel_hi:[1,0]
	v_or_b32_e32 v80, 48, v214
	v_pk_fma_f32 v[84:85], v[76:77], v[164:165], v[82:83] neg_lo:[0,0,1] neg_hi:[0,0,1]
	v_pk_fma_f32 v[76:77], v[76:77], v[164:165], v[82:83] op_sel_hi:[0,1,1]
	v_mov_b32_e32 v76, v79
	v_pk_mul_f32 v[82:83], v[76:77], v[166:167] op_sel:[0,1] op_sel_hi:[0,0]
	v_pk_fma_f32 v[86:87], v[78:79], v[166:167], v[82:83] neg_lo:[0,0,1] neg_hi:[0,0,1]
	v_pk_fma_f32 v[78:79], v[78:79], v[166:167], v[82:83] op_sel_hi:[0,1,1]
	v_pk_mul_f32 v[82:83], v[72:73], v[160:161] op_sel:[1,1] op_sel_hi:[1,0]
	v_ashrrev_i32_e32 v81, 31, v80
	v_pk_fma_f32 v[88:89], v[72:73], v[160:161], v[82:83] neg_lo:[0,0,1] neg_hi:[0,0,1]
	v_pk_fma_f32 v[82:83], v[72:73], v[160:161], v[82:83] op_sel_hi:[0,1,1]
	v_mov_b32_e32 v72, v75
	v_pk_mul_f32 v[72:73], v[72:73], v[162:163] op_sel:[0,1] op_sel_hi:[0,0]
	v_lshlrev_b64 v[80:81], 10, v[80:81]
	v_pk_fma_f32 v[90:91], v[74:75], v[162:163], v[72:73] neg_lo:[0,0,1] neg_hi:[0,0,1]
	v_pk_fma_f32 v[74:75], v[74:75], v[162:163], v[72:73] op_sel_hi:[0,1,1]
	v_lshl_add_u64 v[80:81], v[218:219], 0, v[80:81]
	v_cvt_pk_bf16_f32 v72, v84, v77
	v_cvt_pk_bf16_f32 v73, v86, v79
	v_cvt_pk_bf16_f32 v74, v88, v83
	v_cvt_pk_bf16_f32 v75, v90, v75
	global_store_dwordx4 v[80:81], v[72:75], off sc1 nt
	s_nop 1
	v_pk_mul_f32 v[72:73], v[68:69], v[164:165] op_sel:[1,1] op_sel_hi:[1,0]
	s_nop 0
	v_pk_fma_f32 v[74:75], v[68:69], v[164:165], v[72:73] neg_lo:[0,0,1] neg_hi:[0,0,1]
	v_pk_fma_f32 v[68:69], v[68:69], v[164:165], v[72:73] op_sel_hi:[0,1,1]
	v_mov_b32_e32 v68, v71
	v_pk_mul_f32 v[72:73], v[68:69], v[166:167] op_sel:[0,1] op_sel_hi:[0,0]
	v_pk_fma_f32 v[76:77], v[70:71], v[166:167], v[72:73] neg_lo:[0,0,1] neg_hi:[0,0,1]
	v_pk_fma_f32 v[70:71], v[70:71], v[166:167], v[72:73] op_sel_hi:[0,1,1]
	v_pk_mul_f32 v[72:73], v[64:65], v[160:161] op_sel:[1,1] op_sel_hi:[1,0]
	s_nop 0
	v_pk_fma_f32 v[78:79], v[64:65], v[160:161], v[72:73] neg_lo:[0,0,1] neg_hi:[0,0,1]
	v_pk_fma_f32 v[72:73], v[64:65], v[160:161], v[72:73] op_sel_hi:[0,1,1]
	v_mov_b32_e32 v64, v67
	v_pk_mul_f32 v[64:65], v[64:65], v[162:163] op_sel:[0,1] op_sel_hi:[0,0]
	v_pk_fma_f32 v[82:83], v[66:67], v[162:163], v[64:65] neg_lo:[0,0,1] neg_hi:[0,0,1]
	v_pk_fma_f32 v[66:67], v[66:67], v[162:163], v[64:65] op_sel_hi:[0,1,1]
	v_cvt_pk_bf16_f32 v64, v74, v69
	v_cvt_pk_bf16_f32 v65, v76, v71
	v_cvt_pk_bf16_f32 v66, v78, v73
	v_cvt_pk_bf16_f32 v67, v82, v67
	global_store_dwordx4 v[80:81], v[64:67], off offset:256 sc1 nt
	s_nop 1
	v_pk_mul_f32 v[66:67], v[60:61], v[156:157] op_sel:[1,1] op_sel_hi:[1,0]
	v_lshl_add_u64 v[64:65], v[216:217], 0, s[16:17]
	v_pk_fma_f32 v[68:69], v[60:61], v[156:157], v[66:67] neg_lo:[0,0,1] neg_hi:[0,0,1]
	v_pk_fma_f32 v[60:61], v[60:61], v[156:157], v[66:67] op_sel_hi:[0,1,1]
	v_mov_b32_e32 v60, v63
	v_pk_mul_f32 v[66:67], v[60:61], v[158:159] op_sel:[0,1] op_sel_hi:[0,0]
	v_pk_fma_f32 v[70:71], v[62:63], v[158:159], v[66:67] neg_lo:[0,0,1] neg_hi:[0,0,1]
	v_pk_fma_f32 v[62:63], v[62:63], v[158:159], v[66:67] op_sel_hi:[0,1,1]
	v_pk_mul_f32 v[66:67], v[56:57], v[152:153] op_sel:[1,1] op_sel_hi:[1,0]
	v_add_co_u32_e32 v60, vcc, s71, v216
	v_pk_fma_f32 v[72:73], v[56:57], v[152:153], v[66:67] neg_lo:[0,0,1] neg_hi:[0,0,1]
	v_pk_fma_f32 v[66:67], v[56:57], v[152:153], v[66:67] op_sel_hi:[0,1,1]
	v_mov_b32_e32 v56, v59
	v_pk_mul_f32 v[56:57], v[56:57], v[154:155] op_sel:[0,1] op_sel_hi:[0,0]
	v_pk_fma_f32 v[74:75], v[58:59], v[154:155], v[56:57] neg_lo:[0,0,1] neg_hi:[0,0,1]
	v_pk_fma_f32 v[58:59], v[58:59], v[154:155], v[56:57] op_sel_hi:[0,1,1]
	v_cvt_pk_bf16_f32 v56, v68, v61
	v_cvt_pk_bf16_f32 v57, v70, v63
	v_cvt_pk_bf16_f32 v58, v72, v67
	v_cvt_pk_bf16_f32 v59, v74, v59
	v_addc_co_u32_e32 v61, vcc, 0, v217, vcc
	global_store_dwordx4 v[60:61], v[56:59], off sc1 nt
	s_nop 1
	v_pk_mul_f32 v[56:57], v[52:53], v[156:157] op_sel:[1,1] op_sel_hi:[1,0]
	s_nop 0
	v_pk_fma_f32 v[58:59], v[52:53], v[156:157], v[56:57] neg_lo:[0,0,1] neg_hi:[0,0,1]
	v_pk_fma_f32 v[52:53], v[52:53], v[156:157], v[56:57] op_sel_hi:[0,1,1]
	v_mov_b32_e32 v52, v55
	v_pk_mul_f32 v[56:57], v[52:53], v[158:159] op_sel:[0,1] op_sel_hi:[0,0]
	v_pk_fma_f32 v[60:61], v[54:55], v[158:159], v[56:57] neg_lo:[0,0,1] neg_hi:[0,0,1]
	v_pk_fma_f32 v[54:55], v[54:55], v[158:159], v[56:57] op_sel_hi:[0,1,1]
	v_pk_mul_f32 v[56:57], v[44:45], v[152:153] op_sel:[1,1] op_sel_hi:[1,0]
	s_nop 0
	v_pk_fma_f32 v[62:63], v[44:45], v[152:153], v[56:57] neg_lo:[0,0,1] neg_hi:[0,0,1]
	v_pk_fma_f32 v[56:57], v[44:45], v[152:153], v[56:57] op_sel_hi:[0,1,1]
	v_mov_b32_e32 v44, v47
	v_pk_mul_f32 v[44:45], v[44:45], v[154:155] op_sel:[0,1] op_sel_hi:[0,0]
	v_pk_fma_f32 v[66:67], v[46:47], v[154:155], v[44:45] neg_lo:[0,0,1] neg_hi:[0,0,1]
	v_pk_fma_f32 v[46:47], v[46:47], v[154:155], v[44:45] op_sel_hi:[0,1,1]
	v_cvt_pk_bf16_f32 v44, v58, v53
	v_cvt_pk_bf16_f32 v45, v60, v55
	v_cvt_pk_bf16_f32 v46, v62, v57
	v_cvt_pk_bf16_f32 v47, v66, v47
	global_store_dwordx4 v[64:65], v[44:47], off offset:256 sc1 nt
	s_nop 1
	v_pk_mul_f32 v[46:47], v[48:49], v[148:149] op_sel:[1,1] op_sel_hi:[1,0]
	v_lshl_add_u64 v[44:45], v[216:217], 0, s[18:19]
	v_pk_fma_f32 v[52:53], v[48:49], v[148:149], v[46:47] neg_lo:[0,0,1] neg_hi:[0,0,1]
	v_pk_fma_f32 v[46:47], v[48:49], v[148:149], v[46:47] op_sel_hi:[0,1,1]
	v_mov_b32_e32 v46, v51
	v_pk_mul_f32 v[48:49], v[46:47], v[150:151] op_sel:[0,1] op_sel_hi:[0,0]
	v_pk_fma_f32 v[54:55], v[50:51], v[150:151], v[48:49] neg_lo:[0,0,1] neg_hi:[0,0,1]
	v_pk_fma_f32 v[48:49], v[50:51], v[150:151], v[48:49] op_sel_hi:[0,1,1]
	v_pk_mul_f32 v[50:51], v[40:41], v[144:145] op_sel:[1,1] op_sel_hi:[1,0]
	v_add_co_u32_e32 v46, vcc, s74, v216
	v_pk_fma_f32 v[56:57], v[40:41], v[144:145], v[50:51] neg_lo:[0,0,1] neg_hi:[0,0,1]
	v_pk_fma_f32 v[50:51], v[40:41], v[144:145], v[50:51] op_sel_hi:[0,1,1]
	v_mov_b32_e32 v40, v43
	v_pk_mul_f32 v[40:41], v[40:41], v[146:147] op_sel:[0,1] op_sel_hi:[0,0]
	v_pk_fma_f32 v[58:59], v[42:43], v[146:147], v[40:41] neg_lo:[0,0,1] neg_hi:[0,0,1]
	v_pk_fma_f32 v[42:43], v[42:43], v[146:147], v[40:41] op_sel_hi:[0,1,1]
	v_cvt_pk_bf16_f32 v40, v52, v47
	v_cvt_pk_bf16_f32 v41, v54, v49
	v_cvt_pk_bf16_f32 v42, v56, v51
	v_cvt_pk_bf16_f32 v43, v58, v43
	v_addc_co_u32_e32 v47, vcc, 0, v217, vcc
	global_store_dwordx4 v[46:47], v[40:43], off sc1 nt
	s_nop 1
	v_pk_mul_f32 v[40:41], v[36:37], v[148:149] op_sel:[1,1] op_sel_hi:[1,0]
	s_nop 0
	v_pk_fma_f32 v[42:43], v[36:37], v[148:149], v[40:41] neg_lo:[0,0,1] neg_hi:[0,0,1]
	v_pk_fma_f32 v[36:37], v[36:37], v[148:149], v[40:41] op_sel_hi:[0,1,1]
	v_mov_b32_e32 v36, v39
	v_pk_mul_f32 v[40:41], v[36:37], v[150:151] op_sel:[0,1] op_sel_hi:[0,0]
	v_pk_fma_f32 v[46:47], v[38:39], v[150:151], v[40:41] neg_lo:[0,0,1] neg_hi:[0,0,1]
	v_pk_fma_f32 v[38:39], v[38:39], v[150:151], v[40:41] op_sel_hi:[0,1,1]
	v_pk_mul_f32 v[40:41], v[28:29], v[144:145] op_sel:[1,1] op_sel_hi:[1,0]
	s_nop 0
	v_pk_fma_f32 v[48:49], v[28:29], v[144:145], v[40:41] neg_lo:[0,0,1] neg_hi:[0,0,1]
	v_pk_fma_f32 v[40:41], v[28:29], v[144:145], v[40:41] op_sel_hi:[0,1,1]
	v_mov_b32_e32 v28, v31
	v_pk_mul_f32 v[28:29], v[28:29], v[146:147] op_sel:[0,1] op_sel_hi:[0,0]
	v_pk_fma_f32 v[50:51], v[30:31], v[146:147], v[28:29] neg_lo:[0,0,1] neg_hi:[0,0,1]
	v_pk_fma_f32 v[30:31], v[30:31], v[146:147], v[28:29] op_sel_hi:[0,1,1]
	v_cvt_pk_bf16_f32 v28, v42, v37
	v_cvt_pk_bf16_f32 v29, v46, v39
	v_cvt_pk_bf16_f32 v30, v48, v41
	v_cvt_pk_bf16_f32 v31, v50, v31
	global_store_dwordx4 v[44:45], v[28:31], off offset:256 sc1 nt
	s_nop 1
	v_pk_mul_f32 v[30:31], v[32:33], v[140:141] op_sel:[1,1] op_sel_hi:[1,0]
	v_lshl_add_u64 v[28:29], v[216:217], 0, s[20:21]
	v_pk_fma_f32 v[36:37], v[32:33], v[140:141], v[30:31] neg_lo:[0,0,1] neg_hi:[0,0,1]
	v_pk_fma_f32 v[30:31], v[32:33], v[140:141], v[30:31] op_sel_hi:[0,1,1]
	v_mov_b32_e32 v30, v35
	v_pk_mul_f32 v[32:33], v[30:31], v[142:143] op_sel:[0,1] op_sel_hi:[0,0]
	v_pk_fma_f32 v[38:39], v[34:35], v[142:143], v[32:33] neg_lo:[0,0,1] neg_hi:[0,0,1]
	v_pk_fma_f32 v[32:33], v[34:35], v[142:143], v[32:33] op_sel_hi:[0,1,1]
	v_pk_mul_f32 v[34:35], v[24:25], v[136:137] op_sel:[1,1] op_sel_hi:[1,0]
	v_add_co_u32_e32 v30, vcc, s75, v216
	v_pk_fma_f32 v[40:41], v[24:25], v[136:137], v[34:35] neg_lo:[0,0,1] neg_hi:[0,0,1]
	v_pk_fma_f32 v[34:35], v[24:25], v[136:137], v[34:35] op_sel_hi:[0,1,1]
	v_mov_b32_e32 v24, v27
	v_pk_mul_f32 v[24:25], v[24:25], v[138:139] op_sel:[0,1] op_sel_hi:[0,0]
	v_pk_fma_f32 v[42:43], v[26:27], v[138:139], v[24:25] neg_lo:[0,0,1] neg_hi:[0,0,1]
	v_pk_fma_f32 v[26:27], v[26:27], v[138:139], v[24:25] op_sel_hi:[0,1,1]
	v_cvt_pk_bf16_f32 v24, v36, v31
	v_cvt_pk_bf16_f32 v25, v38, v33
	v_cvt_pk_bf16_f32 v26, v40, v35
	v_cvt_pk_bf16_f32 v27, v42, v27
	v_addc_co_u32_e32 v31, vcc, 0, v217, vcc
	global_store_dwordx4 v[30:31], v[24:27], off sc1 nt
	s_nop 1
	v_pk_mul_f32 v[24:25], v[20:21], v[140:141] op_sel:[1,1] op_sel_hi:[1,0]
	s_nop 0
	v_pk_fma_f32 v[26:27], v[20:21], v[140:141], v[24:25] neg_lo:[0,0,1] neg_hi:[0,0,1]
	v_pk_fma_f32 v[20:21], v[20:21], v[140:141], v[24:25] op_sel_hi:[0,1,1]
	v_mov_b32_e32 v20, v23
	v_pk_mul_f32 v[24:25], v[20:21], v[142:143] op_sel:[0,1] op_sel_hi:[0,0]
	v_pk_fma_f32 v[30:31], v[22:23], v[142:143], v[24:25] neg_lo:[0,0,1] neg_hi:[0,0,1]
	v_pk_fma_f32 v[22:23], v[22:23], v[142:143], v[24:25] op_sel_hi:[0,1,1]
	v_pk_mul_f32 v[24:25], v[12:13], v[136:137] op_sel:[1,1] op_sel_hi:[1,0]
	s_nop 0
	v_pk_fma_f32 v[32:33], v[12:13], v[136:137], v[24:25] neg_lo:[0,0,1] neg_hi:[0,0,1]
	v_pk_fma_f32 v[24:25], v[12:13], v[136:137], v[24:25] op_sel_hi:[0,1,1]
	v_mov_b32_e32 v12, v15
	v_pk_mul_f32 v[12:13], v[12:13], v[138:139] op_sel:[0,1] op_sel_hi:[0,0]
	v_pk_fma_f32 v[34:35], v[14:15], v[138:139], v[12:13] neg_lo:[0,0,1] neg_hi:[0,0,1]
	v_pk_fma_f32 v[14:15], v[14:15], v[138:139], v[12:13] op_sel_hi:[0,1,1]
	v_cvt_pk_bf16_f32 v12, v26, v21
	v_cvt_pk_bf16_f32 v13, v30, v23
	v_cvt_pk_bf16_f32 v14, v32, v25
	v_cvt_pk_bf16_f32 v15, v34, v15
	global_store_dwordx4 v[28:29], v[12:15], off offset:256 sc1 nt
	s_nop 1
	v_pk_mul_f32 v[14:15], v[16:17], v[132:133] op_sel:[1,1] op_sel_hi:[1,0]
	v_lshl_add_u64 v[12:13], v[216:217], 0, s[22:23]
	v_pk_fma_f32 v[20:21], v[16:17], v[132:133], v[14:15] neg_lo:[0,0,1] neg_hi:[0,0,1]
	v_pk_fma_f32 v[14:15], v[16:17], v[132:133], v[14:15] op_sel_hi:[0,1,1]
	v_mov_b32_e32 v14, v19
	v_pk_mul_f32 v[16:17], v[14:15], v[134:135] op_sel:[0,1] op_sel_hi:[0,0]
	v_pk_fma_f32 v[22:23], v[18:19], v[134:135], v[16:17] neg_lo:[0,0,1] neg_hi:[0,0,1]
	v_pk_fma_f32 v[16:17], v[18:19], v[134:135], v[16:17] op_sel_hi:[0,1,1]
	v_pk_mul_f32 v[18:19], v[8:9], v[128:129] op_sel:[1,1] op_sel_hi:[1,0]
	v_add_co_u32_e32 v14, vcc, s78, v216
	v_pk_fma_f32 v[24:25], v[8:9], v[128:129], v[18:19] neg_lo:[0,0,1] neg_hi:[0,0,1]
	v_pk_fma_f32 v[18:19], v[8:9], v[128:129], v[18:19] op_sel_hi:[0,1,1]
	v_mov_b32_e32 v8, v11
	v_pk_mul_f32 v[8:9], v[8:9], v[130:131] op_sel:[0,1] op_sel_hi:[0,0]
	v_pk_fma_f32 v[26:27], v[10:11], v[130:131], v[8:9] neg_lo:[0,0,1] neg_hi:[0,0,1]
	v_pk_fma_f32 v[10:11], v[10:11], v[130:131], v[8:9] op_sel_hi:[0,1,1]
	v_cvt_pk_bf16_f32 v8, v20, v15
	v_cvt_pk_bf16_f32 v9, v22, v17
	v_cvt_pk_bf16_f32 v10, v24, v19
	v_cvt_pk_bf16_f32 v11, v26, v11
	v_addc_co_u32_e32 v15, vcc, 0, v217, vcc
	global_store_dwordx4 v[14:15], v[8:11], off sc1 nt
	s_nop 1
	v_pk_mul_f32 v[8:9], v[4:5], v[132:133] op_sel:[1,1] op_sel_hi:[1,0]
	s_nop 0
	v_pk_fma_f32 v[10:11], v[4:5], v[132:133], v[8:9] neg_lo:[0,0,1] neg_hi:[0,0,1]
	v_pk_fma_f32 v[4:5], v[4:5], v[132:133], v[8:9] op_sel_hi:[0,1,1]
	v_mov_b32_e32 v4, v7
	v_pk_mul_f32 v[8:9], v[4:5], v[134:135] op_sel:[0,1] op_sel_hi:[0,0]
	v_pk_fma_f32 v[14:15], v[6:7], v[134:135], v[8:9] neg_lo:[0,0,1] neg_hi:[0,0,1]
	v_pk_fma_f32 v[6:7], v[6:7], v[134:135], v[8:9] op_sel_hi:[0,1,1]
	v_pk_mul_f32 v[8:9], v[0:1], v[128:129] op_sel:[1,1] op_sel_hi:[1,0]
	s_nop 0
	v_pk_fma_f32 v[16:17], v[0:1], v[128:129], v[8:9] neg_lo:[0,0,1] neg_hi:[0,0,1]
	v_pk_fma_f32 v[8:9], v[0:1], v[128:129], v[8:9] op_sel_hi:[0,1,1]
	v_mov_b32_e32 v0, v3
	v_pk_mul_f32 v[0:1], v[0:1], v[130:131] op_sel:[0,1] op_sel_hi:[0,0]
	v_pk_fma_f32 v[18:19], v[2:3], v[130:131], v[0:1] neg_lo:[0,0,1] neg_hi:[0,0,1]
	v_pk_fma_f32 v[2:3], v[2:3], v[130:131], v[0:1] op_sel_hi:[0,1,1]
	v_cvt_pk_bf16_f32 v0, v10, v5
	v_cvt_pk_bf16_f32 v1, v14, v7
	v_cvt_pk_bf16_f32 v2, v16, v9
	v_cvt_pk_bf16_f32 v3, v18, v3
	global_store_dwordx4 v[12:13], v[0:3], off offset:256 sc1 nt
	s_andn2_b64 vcc, exec, s[4:5]
	s_mov_b64 s[4:5], -1
	s_cbranch_vccnz .LBB0_337
